# P8 pre-norm row loop: next-row prefetch wait moved from mid-row to the end-of-iteration register rotation (counted past the 4 stores issued after the loads)
# speedup vs baseline: 1.0140x; 1.0004x over previous
; __device__ __forceinline__ unsigned pack2(float a, float b) { return (unsigned)f2bf(a) | ((unsigned)f2bf(b) << 16); }
; __device__ __forceinline__ void norm_job(const Params& p, int l, int job, bool from_x) {
;     ...
;   for (int i = 0; i < 16; ++i) {
;     int row = rowbase0 + i;
;     int v = row < MLAT ? (row >> 13) : 2;
;     const float* mods = (const float*)(ws + OFF_MODS) + (l * 3 + v) * 6144;
;     float4 xv[4];
;     xv[0] = nx0; xv[1] = nx1; xv[2] = nx2; xv[3] = nx3;
;     if (i + 1 < 16) {
;       const float* sn = src0 + (size_t)(i + 1) * 1024;
;       nx0 = *(const float4*)&sn[lane * 4]; nx1 = *(const float4*)&sn[lane * 4 + 256];
;       nx2 = *(const float4*)&sn[lane * 4 + 512]; nx3 = *(const float4*)&sn[lane * 4 + 768];
;     }
;     float ss = 0.f;
; #pragma unroll
;     for (int q = 0; q < 4; ++q) {
;       ss += xv[q].x * xv[q].x + xv[q].y * xv[q].y + xv[q].z * xv[q].z + xv[q].w * xv[q].w;
;     }
;     ss = wave_sum(ss);
;     float rstd = rsqrtf(ss * (1.f / 1024.f) + EPSF);
;     if (from_x) {
;       float* dstr = (float*)(ws + OFF_XNEW) + (size_t)row * 1024;
; #pragma unroll
;       for (int q = 0; q < 4; ++q) *(float4*)&dstr[lane * 4 + 256 * q] = xv[q];
;     } else if (row < MLAT) {
;       float* dstr = p.out + (size_t)row * 1024;
; #pragma unroll
;       for (int q = 0; q < 4; ++q) *(float4*)&dstr[lane * 4 + 256 * q] = xv[q];
;     }
; #pragma unroll
;     for (int q = 0; q < 4; ++q) {
;       int col = lane * 4 + 256 * q;
;       float4 w = *(const float4*)&nw[col];
;       float4 sh = *(const float4*)&mods[col];
;       float4 sc = *(const float4*)&mods[1024 + col];
;       float o0 = xv[q].x * rstd * w.x * (1.f + sc.x) + sh.x;
;       float o1 = xv[q].y * rstd * w.y * (1.f + sc.y) + sh.y;
;       float o2 = xv[q].z * rstd * w.z * (1.f + sc.z) + sh.z;
;       float o3 = xv[q].w * rstd * w.w * (1.f + sc.w) + sh.w;
;       uint2 o; o.x = pack2(o0, o1); o.y = pack2(o2, o3);
;       *(uint2*)&HL[(size_t)row * 1024 + col] = o;
;     }
.LBB0_2025:
	s_or_b64 exec, exec, s[10:11]
	v_cndmask_b32_e32 v58, 2, v37, vcc
	v_add_u32_e32 v58, s12, v58
	s_movk_i32 s1, 0x1800
	v_mul_lo_u32 v62, v58, s1
	v_ashrrev_i32_e32 v63, 31, v62
	v_lshl_add_u64 v[70:71], v[62:63], 2, v[42:43]
	s_movk_i32 s1, 0x1000
	v_add_co_u32_e32 v72, vcc, s1, v70
	v_mov_b64_e32 v[58:59], v[186:187]
	v_mov_b64_e32 v[60:61], v[188:189]
	s_nop 0
	v_addc_co_u32_e32 v73, vcc, 0, v71, vcc
	v_mov_b64_e32 v[62:63], v[190:191]
	v_mov_b64_e32 v[64:65], v[192:193]
	v_mov_b64_e32 v[66:67], v[212:213]
	v_mov_b64_e32 v[68:69], v[214:215]
	s_waitcnt lgkmcnt(0)
	v_add_f32_e32 v0, v0, v57
	v_fmamk_f32 v0, v0, 0x3a800000, v197
	v_mov_b32_e32 v74, v30
	v_mul_f32_e32 v30, 0x4b800000, v0
	v_cmp_gt_f32_e32 vcc, s92, v0
	v_lshlrev_b64 v[50:51], 11, v[50:51]
	v_mov_b32_e32 v75, v32
	v_cndmask_b32_e32 v0, v0, v30, vcc
	v_rsq_f32_e32 v0, v0
	v_mov_b32_e32 v32, v31
	v_lshl_add_u64 v[30:31], v[44:45], 0, v[50:51]
	s_add_u32 s8, s8, 0x1000
	v_mul_f32_e32 v50, 0x45800000, v0
	v_cndmask_b32_e32 v0, v0, v50, vcc
	v_pk_mul_f32 v[50:51], v[74:75], v[0:1] op_sel_hi:[1,0]
	v_pk_mul_f32 v[32:33], v[32:33], v[0:1] op_sel_hi:[1,0]
	s_addc_u32 s9, s9, 0
	s_cmpk_eq_u32 s8, 0xf000
	v_lshl_add_u64 v[48:49], v[48:49], 0, 1
	v_mov_b32_e32 v75, v60
	v_mov_b32_e32 v60, v59
	v_pk_mul_f32 v[32:33], v[32:33], v[60:61]
	v_mov_b32_e32 v74, v58
	v_mov_b32_e32 v61, v68
	v_mov_b32_e32 v68, v67
	v_mov_b32_e32 v58, v62
	v_mov_b32_e32 v59, v64
	v_mov_b32_e32 v64, v63
	v_mov_b32_e32 v60, v66
	v_pk_add_f32 v[62:63], v[68:69], 1.0 op_sel_hi:[1,0]
	v_pk_mul_f32 v[50:51], v[50:51], v[74:75]
	v_pk_add_f32 v[60:61], v[60:61], 1.0 op_sel_hi:[1,0]
	v_pk_fma_f32 v[32:33], v[32:33], v[62:63], v[64:65]
	v_pk_fma_f32 v[50:51], v[50:51], v[60:61], v[58:59]
	v_and_b32_sdwa v59, v33, v198 dst_sel:DWORD dst_unused:UNUSED_PAD src0_sel:WORD_1 src1_sel:DWORD
	v_and_b32_sdwa v60, v32, v198 dst_sel:DWORD dst_unused:UNUSED_PAD src0_sel:WORD_1 src1_sel:DWORD
	v_and_b32_sdwa v57, v51, v198 dst_sel:DWORD dst_unused:UNUSED_PAD src0_sel:WORD_1 src1_sel:DWORD
	v_and_b32_sdwa v58, v50, v198 dst_sel:DWORD dst_unused:UNUSED_PAD src0_sel:WORD_1 src1_sel:DWORD
	v_add3_u32 v33, v33, v59, s33
	v_add3_u32 v32, v32, v60, s33
	v_add3_u32 v50, v50, v58, s33
	v_add3_u32 v51, v51, v57, s33
	v_and_b32_e32 v33, 0xffff0000, v33
	v_and_b32_e32 v32, 0xffff0000, v32
	v_or_b32_sdwa v33, v33, v51 dst_sel:DWORD dst_unused:UNUSED_PAD src0_sel:DWORD src1_sel:WORD_1
	v_or_b32_sdwa v32, v32, v50 dst_sel:DWORD dst_unused:UNUSED_PAD src0_sel:DWORD src1_sel:WORD_1
	global_store_dwordx2 v[30:31], v[32:33], off
	v_mov_b64_e32 v[58:59], v[216:217]
	v_mov_b64_e32 v[60:61], v[218:219]
	v_mov_b64_e32 v[62:63], v[224:225]
	v_mov_b64_e32 v[64:65], v[226:227]
	v_mov_b64_e32 v[66:67], v[220:221]
	v_mov_b64_e32 v[68:69], v[222:223]
	v_mov_b32_e32 v32, v26
	v_mov_b32_e32 v33, v28
	v_mov_b32_e32 v28, v27
	v_pk_mul_f32 v[26:27], v[32:33], v[0:1] op_sel_hi:[1,0]
	v_pk_mul_f32 v[28:29], v[28:29], v[0:1] op_sel_hi:[1,0]
	v_mov_b32_e32 v32, v58
	v_mov_b32_e32 v33, v60
	s_waitcnt lgkmcnt(0)
	v_mov_b32_e32 v50, v62
	v_mov_b32_e32 v51, v64
	v_mov_b32_e32 v60, v59
	v_mov_b32_e32 v64, v63
	v_mov_b32_e32 v75, v68
	v_mov_b32_e32 v68, v67
	v_pk_mul_f32 v[26:27], v[26:27], v[32:33]
	v_pk_add_f32 v[32:33], v[50:51], 1.0 op_sel_hi:[1,0]
	v_pk_mul_f32 v[28:29], v[28:29], v[60:61]
	v_pk_add_f32 v[50:51], v[64:65], 1.0 op_sel_hi:[1,0]
	v_mov_b32_e32 v74, v66
	v_pk_fma_f32 v[28:29], v[28:29], v[50:51], v[68:69]
	v_pk_fma_f32 v[26:27], v[26:27], v[32:33], v[74:75]
	v_and_b32_sdwa v50, v29, v198 dst_sel:DWORD dst_unused:UNUSED_PAD src0_sel:WORD_1 src1_sel:DWORD
	v_and_b32_sdwa v51, v28, v198 dst_sel:DWORD dst_unused:UNUSED_PAD src0_sel:WORD_1 src1_sel:DWORD
	v_and_b32_sdwa v32, v27, v198 dst_sel:DWORD dst_unused:UNUSED_PAD src0_sel:WORD_1 src1_sel:DWORD
	v_and_b32_sdwa v33, v26, v198 dst_sel:DWORD dst_unused:UNUSED_PAD src0_sel:WORD_1 src1_sel:DWORD
	v_add3_u32 v29, v29, v50, s33
	v_add3_u32 v28, v28, v51, s33
	v_add3_u32 v26, v26, v33, s33
	v_add3_u32 v27, v27, v32, s33
	v_and_b32_e32 v29, 0xffff0000, v29
	v_and_b32_e32 v28, 0xffff0000, v28
	v_or_b32_sdwa v27, v29, v27 dst_sel:DWORD dst_unused:UNUSED_PAD src0_sel:DWORD src1_sel:WORD_1
	v_or_b32_sdwa v26, v28, v26 dst_sel:DWORD dst_unused:UNUSED_PAD src0_sel:DWORD src1_sel:WORD_1
	global_store_dwordx2 v[30:31], v[26:27], off offset:512
	v_mov_b64_e32 v[26:27], v[228:229]
	v_mov_b64_e32 v[28:29], v[230:231]
	s_nop 0
	v_mov_b64_e32 v[58:59], v[240:241]
	v_mov_b64_e32 v[60:61], v[242:243]
	v_mov_b64_e32 v[62:63], v[232:233]
	v_mov_b64_e32 v[64:65], v[234:235]
	v_mov_b32_e32 v32, v22
	v_mov_b32_e32 v33, v24
	v_mov_b32_e32 v24, v23
	v_pk_mul_f32 v[22:23], v[32:33], v[0:1] op_sel_hi:[1,0]
	v_pk_mul_f32 v[24:25], v[24:25], v[0:1] op_sel_hi:[1,0]
	v_mov_b32_e32 v33, v28
	s_waitcnt lgkmcnt(0)
; __device__ __forceinline__ unsigned pack2(float a, float b) { return (unsigned)f2bf(a) | ((unsigned)f2bf(b) << 16); }
; __device__ __forceinline__ void norm_job(const Params& p, int l, int job, bool from_x) {
;     ...
;   for (int i = 0; i < 16; ++i) {
;     int row = rowbase0 + i;
;     int v = row < MLAT ? (row >> 13) : 2;
;     const float* mods = (const float*)(ws + OFF_MODS) + (l * 3 + v) * 6144;
;     float4 xv[4];
;     xv[0] = nx0; xv[1] = nx1; xv[2] = nx2; xv[3] = nx3;
;     if (i + 1 < 16) {
;       const float* sn = src0 + (size_t)(i + 1) * 1024;
;       nx0 = *(const float4*)&sn[lane * 4]; nx1 = *(const float4*)&sn[lane * 4 + 256];
;       nx2 = *(const float4*)&sn[lane * 4 + 512]; nx3 = *(const float4*)&sn[lane * 4 + 768];
;     }
;     float ss = 0.f;
; #pragma unroll
;     for (int q = 0; q < 4; ++q) {
;       ss += xv[q].x * xv[q].x + xv[q].y * xv[q].y + xv[q].z * xv[q].z + xv[q].w * xv[q].w;
;     }
;     ss = wave_sum(ss);
;     float rstd = rsqrtf(ss * (1.f / 1024.f) + EPSF);
;     if (from_x) {
;       float* dstr = (float*)(ws + OFF_XNEW) + (size_t)row * 1024;
; #pragma unroll
;       for (int q = 0; q < 4; ++q) *(float4*)&dstr[lane * 4 + 256 * q] = xv[q];
;     } else if (row < MLAT) {
;       float* dstr = p.out + (size_t)row * 1024;
; #pragma unroll
;       for (int q = 0; q < 4; ++q) *(float4*)&dstr[lane * 4 + 256 * q] = xv[q];
;     }
; #pragma unroll
;     for (int q = 0; q < 4; ++q) {
;       int col = lane * 4 + 256 * q;
;       float4 w = *(const float4*)&nw[col];
;       float4 sh = *(const float4*)&mods[col];
;       float4 sc = *(const float4*)&mods[1024 + col];
;       float o0 = xv[q].x * rstd * w.x * (1.f + sc.x) + sh.x;
;       float o1 = xv[q].y * rstd * w.y * (1.f + sc.y) + sh.y;
;       float o2 = xv[q].z * rstd * w.z * (1.f + sc.z) + sh.z;
;       float o3 = xv[q].w * rstd * w.w * (1.f + sc.w) + sh.w;
;       uint2 o; o.x = pack2(o0, o1); o.y = pack2(o2, o3);
;       *(uint2*)&HL[(size_t)row * 1024 + col] = o;
;     }
	v_mov_b32_e32 v51, v60
	v_mov_b32_e32 v28, v27
	v_mov_b32_e32 v60, v59
	v_mov_b32_e32 v32, v26
	v_mov_b32_e32 v50, v58
	v_mov_b32_e32 v67, v64
	v_mov_b32_e32 v64, v63
	v_pk_mul_f32 v[24:25], v[24:25], v[28:29]
	v_pk_add_f32 v[28:29], v[60:61], 1.0 op_sel_hi:[1,0]
	v_mov_b32_e32 v66, v62
	v_pk_mul_f32 v[22:23], v[22:23], v[32:33]
	v_pk_add_f32 v[26:27], v[50:51], 1.0 op_sel_hi:[1,0]
	v_pk_fma_f32 v[24:25], v[24:25], v[28:29], v[64:65]
	v_pk_fma_f32 v[22:23], v[22:23], v[26:27], v[66:67]
	v_and_b32_sdwa v28, v25, v198 dst_sel:DWORD dst_unused:UNUSED_PAD src0_sel:WORD_1 src1_sel:DWORD
	v_and_b32_sdwa v29, v24, v198 dst_sel:DWORD dst_unused:UNUSED_PAD src0_sel:WORD_1 src1_sel:DWORD
	v_and_b32_sdwa v26, v23, v198 dst_sel:DWORD dst_unused:UNUSED_PAD src0_sel:WORD_1 src1_sel:DWORD
	v_and_b32_sdwa v27, v22, v198 dst_sel:DWORD dst_unused:UNUSED_PAD src0_sel:WORD_1 src1_sel:DWORD
	v_add3_u32 v25, v25, v28, s33
	v_add3_u32 v24, v24, v29, s33
	v_add3_u32 v22, v22, v27, s33
	v_add3_u32 v23, v23, v26, s33
	v_and_b32_e32 v25, 0xffff0000, v25
	v_and_b32_e32 v24, 0xffff0000, v24
	v_or_b32_sdwa v23, v25, v23 dst_sel:DWORD dst_unused:UNUSED_PAD src0_sel:DWORD src1_sel:WORD_1
	v_or_b32_sdwa v22, v24, v22 dst_sel:DWORD dst_unused:UNUSED_PAD src0_sel:DWORD src1_sel:WORD_1
	global_store_dwordx2 v[30:31], v[22:23], off offset:1024
	v_mov_b64_e32 v[22:23], v[244:245]
	v_mov_b64_e32 v[24:25], v[246:247]
	s_nop 0
	v_mov_b64_e32 v[26:27], v[252:253]
	v_mov_b64_e32 v[28:29], v[254:255]
	v_mov_b64_e32 v[58:59], v[248:249]
	v_mov_b64_e32 v[60:61], v[250:251]
	v_mov_b32_e32 v32, v18
	v_mov_b32_e32 v33, v20
	v_mov_b32_e32 v20, v19
	v_pk_mul_f32 v[18:19], v[32:33], v[0:1] op_sel_hi:[1,0]
	v_pk_mul_f32 v[20:21], v[20:21], v[0:1] op_sel_hi:[1,0]
	v_mov_b32_e32 v32, v22
	v_mov_b32_e32 v33, v24
	s_waitcnt lgkmcnt(0)
	v_mov_b32_e32 v50, v26
	v_mov_b32_e32 v51, v28
	v_mov_b32_e32 v24, v23
	v_mov_b32_e32 v28, v27
	v_mov_b32_e32 v62, v58
	v_mov_b32_e32 v63, v60
	v_mov_b32_e32 v60, v59
	v_pk_mul_f32 v[18:19], v[18:19], v[32:33]
	v_pk_add_f32 v[22:23], v[50:51], 1.0 op_sel_hi:[1,0]
	v_pk_mul_f32 v[20:21], v[20:21], v[24:25]
	v_pk_add_f32 v[24:25], v[28:29], 1.0 op_sel_hi:[1,0]
	v_pk_fma_f32 v[18:19], v[18:19], v[22:23], v[62:63]
	v_pk_fma_f32 v[20:21], v[20:21], v[24:25], v[60:61]
	v_and_b32_sdwa v0, v19, v198 dst_sel:DWORD dst_unused:UNUSED_PAD src0_sel:WORD_1 src1_sel:DWORD
	v_and_b32_sdwa v23, v21, v198 dst_sel:DWORD dst_unused:UNUSED_PAD src0_sel:WORD_1 src1_sel:DWORD
	v_and_b32_sdwa v24, v20, v198 dst_sel:DWORD dst_unused:UNUSED_PAD src0_sel:WORD_1 src1_sel:DWORD
	v_and_b32_sdwa v22, v18, v198 dst_sel:DWORD dst_unused:UNUSED_PAD src0_sel:WORD_1 src1_sel:DWORD
	v_add3_u32 v0, v19, v0, s33
	v_add3_u32 v19, v21, v23, s33
	v_add3_u32 v20, v20, v24, s33
	v_add3_u32 v18, v18, v22, s33
	v_and_b32_e32 v19, 0xffff0000, v19
	v_and_b32_e32 v20, 0xffff0000, v20
	v_or_b32_sdwa v19, v19, v0 dst_sel:DWORD dst_unused:UNUSED_PAD src0_sel:DWORD src1_sel:WORD_1
	v_or_b32_sdwa v18, v20, v18 dst_sel:DWORD dst_unused:UNUSED_PAD src0_sel:DWORD src1_sel:WORD_1
	global_store_dwordx2 v[30:31], v[18:19], off offset:1536
	s_cbranch_scc1 .LBB0_2027
	s_waitcnt vmcnt(4)
	v_mov_b64_e32 v[32:33], v[16:17]
	v_mov_b64_e32 v[28:29], v[12:13]
	v_mov_b64_e32 v[24:25], v[8:9]
	v_mov_b64_e32 v[20:21], v[4:5]
	v_mov_b64_e32 v[30:31], v[14:15]
	v_mov_b64_e32 v[26:27], v[10:11]
	v_mov_b64_e32 v[22:23], v[6:7]
	v_mov_b64_e32 v[18:19], v[2:3]
	s_branch .LBB0_2023
.LBB0_2027:
	s_waitcnt vmcnt(4)
	v_mul_f32_e32 v0, v15, v15
	v_mul_f32_e32 v18, v11, v11
	v_fmac_f32_e32 v0, v14, v14
	v_fmac_f32_e32 v18, v10, v10
	v_fmac_f32_e32 v0, v16, v16
	v_fmac_f32_e32 v18, v12, v12
	v_fmac_f32_e32 v0, v17, v17
	v_fmac_f32_e32 v18, v13, v13
	v_add_f32_e32 v0, v0, v18
	v_mul_f32_e32 v18, v7, v7
	v_fmac_f32_e32 v18, v6, v6
	v_fmac_f32_e32 v18, v8, v8
	v_fmac_f32_e32 v18, v9, v9
	v_add_f32_e32 v0, v0, v18
	v_mul_f32_e32 v18, v3, v3
	v_fmac_f32_e32 v18, v2, v2
	v_fmac_f32_e32 v18, v4, v4
	v_fmac_f32_e32 v18, v5, v5
	v_add_f32_e32 v0, v0, v18
	ds_bpermute_b32 v18, v39, v0
	s_movk_i32 s1, 0x3fff
	s_waitcnt lgkmcnt(0)
	v_add_f32_e32 v0, v0, v18
	ds_bpermute_b32 v18, v52, v0
	s_waitcnt lgkmcnt(0)
	v_add_f32_e32 v0, v0, v18
	ds_bpermute_b32 v18, v53, v0
	s_waitcnt lgkmcnt(0)
	v_add_f32_e32 v0, v0, v18
	ds_bpermute_b32 v18, v54, v0
	s_waitcnt lgkmcnt(0)
	v_add_f32_e32 v0, v0, v18
	ds_bpermute_b32 v18, v55, v0
	s_waitcnt lgkmcnt(0)
	v_add_f32_e32 v20, v0, v18
	ds_bpermute_b32 v21, v56, v20
	v_or_b32_e32 v18, 15, v38
	v_cmp_lt_i32_e32 vcc, s1, v18
	s_and_saveexec_b64 s[8:9], vcc
	s_xor_b64 s[8:9], exec, s[8:9]
	v_mov_b32_e32 v19, v1
	s_or_saveexec_b64 s[8:9], s[8:9]
	v_mov_b32_e32 v22, 2
	v_lshlrev_b32_e32 v0, 2, v36
	s_xor_b64 exec, exec, s[8:9]
	s_cbranch_execz .LBB0_2021
	v_ashrrev_i32_e32 v19, 31, v18
	v_lshlrev_b64 v[22:23], 12, v[18:19]
	v_lshl_add_u64 v[22:23], s[56:57], 0, v[22:23]
	v_mov_b32_e32 v24, v0
	v_mov_b32_e32 v25, v1
	v_lshl_add_u64 v[22:23], v[22:23], 0, v[24:25]
	v_mov_b32_e32 v22, v37
	s_branch .LBB0_2021
